# stacked item-phase latency edits (retb output-stage load batching, conv LN gain/bias hoist, la_items transpose LDS reads + counted waits) under the tail-unit pipeline
# speedup vs baseline: 1.0152x; 1.0045x over previous
.LBB0_715:
	s_cmp_gt_i32 s34, 48
	s_cselect_b32 s0, 24, 0
	s_cmp_lt_i32 s2, s0
	s_cbranch_scc1 .LBB0_782
	s_sub_i32 s1, s34, s0
	s_abs_i32 s3, s1
	s_waitcnt vmcnt(0)
	v_cvt_f32_u32_e32 v0, s3
	s_sub_i32 s5, 0, s3
	s_sub_i32 s4, s2, s0
	s_ashr_i32 s0, s1, 31
	v_rcp_iflag_f32_e32 v0, v0
	s_nop 0
	v_mul_f32_e32 v0, 0x4f7ffffe, v0
	v_cvt_u32_f32_e32 v0, v0
	s_nop 0
	v_readfirstlane_b32 s6, v0
	s_mul_i32 s5, s5, s6
	s_mul_hi_u32 s5, s6, s5
	s_add_i32 s6, s6, s5
	s_lshr_b32 s5, s6, 22
	s_mul_i32 s6, s5, s3
	s_sub_i32 s6, 0x400, s6
	s_add_i32 s7, s5, 1
	s_sub_i32 s8, s6, s3
	s_cmp_ge_u32 s6, s3
	s_cselect_b32 s5, s7, s5
	s_cselect_b32 s6, s8, s6
	s_add_i32 s7, s5, 1
	s_cmp_ge_u32 s6, s3
	s_cselect_b32 s3, s7, s5
	s_xor_b32 s3, s3, s0
	s_sub_i32 s5, s3, s0
	s_mul_i32 s0, s5, s1
	s_sub_i32 s6, 0x400, s0
	s_cmp_lt_i32 s4, s6
	s_mul_i32 s3, s5, s4
	s_cselect_b64 s[0:1], -1, 0
	s_min_i32 s4, s4, s6
	s_add_i32 s3, s4, s3
	s_cmp_lg_u64 s[0:1], 0
	s_addc_u32 s10, s3, s5
	s_add_i32 s1, s3, 1
	s_add_i32 s4, s10, 1
	s_ashr_i32 s0, s1, 1
	s_ashr_i32 s11, s4, 1
	s_cmp_ge_i32 s0, s11
	s_cbranch_scc1 .LBB0_726
	v_readfirstlane_b32 s4, v175
	s_lshr_b32 s8, s4, 6
	s_ashr_i32 s4, s1, 7
	s_ashr_i32 s5, s4, 31
	s_lshl_b32 s6, s0, 17
	s_lshl_b64 s[4:5], s[4:5], 21
	s_and_b32 s6, s6, 0x1e0000
	s_lshl_b32 s1, s0, 16
	s_or_b32 s4, s4, s6
	s_add_u32 s6, s36, s4
	s_addc_u32 s7, s37, s5
	s_lshl_b32 s12, s0, 4
	s_lshl_b32 s9, s0, 3
	s_and_b32 s12, s12, 0x300
	s_add_u32 s6, s6, s12
	s_addc_u32 s7, s7, 0
	s_add_u32 s4, s38, s4
	v_lshlrev_b32_e32 v0, 7, v175
	s_addc_u32 s5, s39, s5
	v_and_b32_e32 v36, 0x1fe00, v0
	v_lshlrev_b32_e32 v2, 5, v175
	s_add_u32 s4, s4, s12
	v_mov_b32_e32 v33, 0
	v_lshlrev_b32_e32 v32, 1, v36
	v_and_b32_e32 v42, 0x60, v2
	s_addc_u32 s5, s5, 0
	v_lshl_add_u64 v[0:1], s[6:7], 0, v[32:33]
	v_lshlrev_b32_e32 v34, 1, v42
	v_mov_b32_e32 v35, v33
	v_lshl_add_u64 v[16:17], s[4:5], 0, v[32:33]
	v_lshl_add_u64 v[12:13], v[0:1], 0, v[34:35]
	v_lshl_add_u64 v[28:29], v[16:17], 0, v[34:35]
	global_load_dwordx4 v[0:3], v[12:13], off offset:48
	global_load_dwordx4 v[4:7], v[12:13], off offset:32
	global_load_dwordx4 v[8:11], v[12:13], off offset:16
	s_nop 0
	global_load_dwordx4 v[12:15], v[12:13], off
	s_nop 0
	global_load_dwordx4 v[16:19], v[28:29], off offset:48
	global_load_dwordx4 v[20:23], v[28:29], off offset:32
	global_load_dwordx4 v[24:27], v[28:29], off offset:16
	s_nop 0
	global_load_dwordx4 v[28:31], v[28:29], off
	v_and_b32_e32 v32, 15, v175
	v_lshrrev_b32_e32 v35, 2, v175
	v_add_u32_e32 v37, 0, v34
	v_lshl_add_u32 v34, v32, 1, 0
	v_sub_u32_e32 v38, 0x7f, v35
	s_movk_i32 s4, 0x108
	v_mul_u32_u24_e32 v43, 0x120, v35
	v_and_b32_e32 v35, 12, v35
	v_lshlrev_b32_e32 v32, 7, v32
	s_add_i32 s13, s1, 0x10000
	s_ashr_i32 s1, s0, 31
	v_mad_u32_u24 v39, v35, s4, v34
	s_lshl_b64 s[4:5], s[0:1], 16
	v_lshl_or_b32 v40, s8, 11, v32
	v_cvt_f32_i32_e32 v38, v38
	v_lshl_add_u32 v44, s8, 5, v34
	v_mul_u32_u24_e32 v45, 0x108, v35
	v_and_or_b32 v34, v175, 48, s4
	v_mov_b32_e32 v35, s5
	v_ashrrev_i32_e32 v41, 31, v40
	v_lshl_add_u64 v[34:35], v[40:41], 2, v[34:35]
	v_lshl_add_u64 v[34:35], s[94:95], 0, v[34:35]
	s_mov_b64 s[4:5], 0x100100
	s_add_i32 s12, s9, 8
	v_lshl_add_u64 v[34:35], v[34:35], 0, s[4:5]
	v_add_u32_e32 v40, v37, v43
	v_lshlrev_b32_e32 v32, 1, v36
	v_lshlrev_b32_e32 v36, 1, v42
	v_add_u32_e32 v41, v44, v45
	s_mov_b32 s1, 0x5040100
	s_mov_b64 s[4:5], 0x10000
	v_mov_b32_e32 v42, 0xbbb906ce
	v_mov_b32_e32 v43, 0xbc3963dd
	s_waitcnt vmcnt(0)
	s_branch .LBB0_719
.LBB0_718:
	s_waitcnt lgkmcnt(0)
	s_barrier
	s_add_i32 s12, s12, 8
	s_add_i32 s13, s13, 0x10000
	s_andn2_b64 vcc, exec, s[8:9]
	v_and_b32_e32 v226, 63, v175
	v_bfe_u32 v227, v226, 2, 4
	v_mul_u32_u24_e32 v227, 0x120, v227
	v_and_b32_e32 v226, 3, v226
	v_lshl_add_u32 v227, v226, 3, v227
	v_lshrrev_b32_e32 v226, 6, v175
	v_lshl_add_u32 v226, v226, 5, v227
	v_add_u32_e32 v227, 0x9000, v227
	ds_read_b64_tr_b16 v[76:77], v226
	ds_read_b64_tr_b16 v[78:79], v226 offset:4608
	ds_read_b64_tr_b16 v[80:81], v226 offset:9216
	ds_read_b64_tr_b16 v[82:83], v226 offset:13824
	ds_read_b64_tr_b16 v[116:117], v226 offset:18432
	ds_read_b64_tr_b16 v[118:119], v226 offset:23040
	ds_read_b64_tr_b16 v[120:121], v226 offset:27648
	ds_read_b64_tr_b16 v[122:123], v226 offset:32256
	ds_read_b64_tr_b16 v[84:85], v227
	ds_read_b64_tr_b16 v[86:87], v227 offset:4608
	ds_read_b64_tr_b16 v[88:89], v227 offset:32
	ds_read_b64_tr_b16 v[90:91], v227 offset:4640
	ds_read_b64_tr_b16 v[92:93], v227 offset:64
	ds_read_b64_tr_b16 v[94:95], v227 offset:4672
	ds_read_b64_tr_b16 v[96:97], v227 offset:96
	ds_read_b64_tr_b16 v[98:99], v227 offset:4704
	ds_read_b64_tr_b16 v[100:101], v227 offset:128
	ds_read_b64_tr_b16 v[102:103], v227 offset:4736
	ds_read_b64_tr_b16 v[104:105], v227 offset:160
	ds_read_b64_tr_b16 v[106:107], v227 offset:4768
	ds_read_b64_tr_b16 v[108:109], v227 offset:192
	ds_read_b64_tr_b16 v[110:111], v227 offset:4800
	ds_read_b64_tr_b16 v[112:113], v227 offset:224
	ds_read_b64_tr_b16 v[114:115], v227 offset:4832
	s_waitcnt lgkmcnt(14)
	v_mfma_f32_16x16x32_bf16 v[44:47], v[84:87], v[76:79], 0
	ds_read_b64_tr_b16 v[84:85], v227 offset:9216
	ds_read_b64_tr_b16 v[86:87], v227 offset:13824
	s_waitcnt lgkmcnt(14)
	v_mfma_f32_16x16x32_bf16 v[52:55], v[88:91], v[76:79], 0
	ds_read_b64_tr_b16 v[88:89], v227 offset:9248
	ds_read_b64_tr_b16 v[90:91], v227 offset:13856
	s_waitcnt lgkmcnt(14)
	v_mfma_f32_16x16x32_bf16 v[56:59], v[92:95], v[76:79], 0
	ds_read_b64_tr_b16 v[92:93], v227 offset:9280
	ds_read_b64_tr_b16 v[94:95], v227 offset:13888
	s_waitcnt lgkmcnt(14)
	v_mfma_f32_16x16x32_bf16 v[60:63], v[96:99], v[76:79], 0
	ds_read_b64_tr_b16 v[96:97], v227 offset:9312
	ds_read_b64_tr_b16 v[98:99], v227 offset:13920
	s_waitcnt lgkmcnt(14)
	v_mfma_f32_16x16x32_bf16 v[64:67], v[100:103], v[76:79], 0
	ds_read_b64_tr_b16 v[100:101], v227 offset:9344
	ds_read_b64_tr_b16 v[102:103], v227 offset:13952
	s_waitcnt lgkmcnt(14)
	v_mfma_f32_16x16x32_bf16 v[68:71], v[104:107], v[76:79], 0
	ds_read_b64_tr_b16 v[104:105], v227 offset:9376
	ds_read_b64_tr_b16 v[106:107], v227 offset:13984
	s_waitcnt lgkmcnt(14)
	v_mfma_f32_16x16x32_bf16 v[72:75], v[108:111], v[76:79], 0
	ds_read_b64_tr_b16 v[108:109], v227 offset:9408
	ds_read_b64_tr_b16 v[110:111], v227 offset:14016
	s_waitcnt lgkmcnt(14)
	v_mfma_f32_16x16x32_bf16 v[48:51], v[112:115], v[76:79], 0
	ds_read_b64_tr_b16 v[112:113], v227 offset:9440
	ds_read_b64_tr_b16 v[114:115], v227 offset:14048
	s_waitcnt lgkmcnt(14)
	v_mfma_f32_16x16x32_bf16 v[44:47], v[84:87], v[80:83], v[44:47]
	ds_read_b64_tr_b16 v[84:85], v227 offset:18432
	ds_read_b64_tr_b16 v[86:87], v227 offset:23040
	s_waitcnt lgkmcnt(14)
	v_mfma_f32_16x16x32_bf16 v[52:55], v[88:91], v[80:83], v[52:55]
	ds_read_b64_tr_b16 v[88:89], v227 offset:18464
	ds_read_b64_tr_b16 v[90:91], v227 offset:23072
	s_waitcnt lgkmcnt(14)
	v_mfma_f32_16x16x32_bf16 v[56:59], v[92:95], v[80:83], v[56:59]
	ds_read_b64_tr_b16 v[92:93], v227 offset:18496
	ds_read_b64_tr_b16 v[94:95], v227 offset:23104
	s_waitcnt lgkmcnt(14)
	v_mfma_f32_16x16x32_bf16 v[60:63], v[96:99], v[80:83], v[60:63]
	ds_read_b64_tr_b16 v[96:97], v227 offset:18528
	ds_read_b64_tr_b16 v[98:99], v227 offset:23136
	s_waitcnt lgkmcnt(14)
	v_mfma_f32_16x16x32_bf16 v[64:67], v[100:103], v[80:83], v[64:67]
	ds_read_b64_tr_b16 v[100:101], v227 offset:18560
	ds_read_b64_tr_b16 v[102:103], v227 offset:23168
	s_waitcnt lgkmcnt(14)
	v_mfma_f32_16x16x32_bf16 v[68:71], v[104:107], v[80:83], v[68:71]
	ds_read_b64_tr_b16 v[104:105], v227 offset:18592
	ds_read_b64_tr_b16 v[106:107], v227 offset:23200
	s_waitcnt lgkmcnt(14)
	v_mfma_f32_16x16x32_bf16 v[72:75], v[108:111], v[80:83], v[72:75]
	ds_read_b64_tr_b16 v[108:109], v227 offset:18624
	ds_read_b64_tr_b16 v[110:111], v227 offset:23232
	s_waitcnt lgkmcnt(14)
	v_mfma_f32_16x16x32_bf16 v[48:51], v[112:115], v[80:83], v[48:51]
	ds_read_b64_tr_b16 v[112:113], v227 offset:18656
	ds_read_b64_tr_b16 v[114:115], v227 offset:23264
	s_waitcnt lgkmcnt(14)
	v_mfma_f32_16x16x32_bf16 v[44:47], v[84:87], v[116:119], v[44:47]
	ds_read_b64_tr_b16 v[84:85], v227 offset:27648
	ds_read_b64_tr_b16 v[86:87], v227 offset:32256
	s_waitcnt lgkmcnt(14)
	v_mfma_f32_16x16x32_bf16 v[52:55], v[88:91], v[116:119], v[52:55]
	ds_read_b64_tr_b16 v[88:89], v227 offset:27680
	ds_read_b64_tr_b16 v[90:91], v227 offset:32288
	s_waitcnt lgkmcnt(14)
	v_mfma_f32_16x16x32_bf16 v[56:59], v[92:95], v[116:119], v[56:59]
	ds_read_b64_tr_b16 v[92:93], v227 offset:27712
	ds_read_b64_tr_b16 v[94:95], v227 offset:32320
	s_waitcnt lgkmcnt(14)
	v_mfma_f32_16x16x32_bf16 v[60:63], v[96:99], v[116:119], v[60:63]
	ds_read_b64_tr_b16 v[96:97], v227 offset:27744
	ds_read_b64_tr_b16 v[98:99], v227 offset:32352
	s_waitcnt lgkmcnt(14)
	v_mfma_f32_16x16x32_bf16 v[64:67], v[100:103], v[116:119], v[64:67]
	ds_read_b64_tr_b16 v[100:101], v227 offset:27776
	ds_read_b64_tr_b16 v[102:103], v227 offset:32384
	s_waitcnt lgkmcnt(14)
	v_mfma_f32_16x16x32_bf16 v[68:71], v[104:107], v[116:119], v[68:71]
	ds_read_b64_tr_b16 v[104:105], v227 offset:27808
	ds_read_b64_tr_b16 v[106:107], v227 offset:32416
	s_waitcnt lgkmcnt(14)
	v_mfma_f32_16x16x32_bf16 v[72:75], v[108:111], v[116:119], v[72:75]
	ds_read_b64_tr_b16 v[108:109], v227 offset:27840
	ds_read_b64_tr_b16 v[110:111], v227 offset:32448
	s_waitcnt lgkmcnt(14)
	v_mfma_f32_16x16x32_bf16 v[48:51], v[112:115], v[116:119], v[48:51]
	ds_read_b64_tr_b16 v[112:113], v227 offset:27872
	ds_read_b64_tr_b16 v[114:115], v227 offset:32480
	s_waitcnt lgkmcnt(14)
	v_mfma_f32_16x16x32_bf16 v[44:47], v[84:87], v[120:123], v[44:47]
	s_waitcnt lgkmcnt(12)
	v_mfma_f32_16x16x32_bf16 v[52:55], v[88:91], v[120:123], v[52:55]
	s_waitcnt lgkmcnt(10)
	v_mfma_f32_16x16x32_bf16 v[56:59], v[92:95], v[120:123], v[56:59]
	s_waitcnt lgkmcnt(8)
	v_mfma_f32_16x16x32_bf16 v[60:63], v[96:99], v[120:123], v[60:63]
	s_waitcnt lgkmcnt(6)
	v_mfma_f32_16x16x32_bf16 v[64:67], v[100:103], v[120:123], v[64:67]
	s_waitcnt lgkmcnt(4)
	v_mfma_f32_16x16x32_bf16 v[68:71], v[104:107], v[120:123], v[68:71]
	s_waitcnt lgkmcnt(2)
	v_mfma_f32_16x16x32_bf16 v[72:75], v[108:111], v[120:123], v[72:75]
	s_waitcnt lgkmcnt(0)
	v_mfma_f32_16x16x32_bf16 v[48:51], v[112:115], v[120:123], v[48:51]
	global_store_dwordx4 v[34:35], v[44:47], off offset:-256
	global_store_dwordx4 v[34:35], v[52:55], off offset:-192
	global_store_dwordx4 v[34:35], v[56:59], off offset:-128
	global_store_dwordx4 v[34:35], v[60:63], off offset:-64
	global_store_dwordx4 v[34:35], v[64:67], off
	global_store_dwordx4 v[34:35], v[68:71], off offset:64
	global_store_dwordx4 v[34:35], v[72:75], off offset:128
	s_nop 0
	global_store_dwordx4 v[34:35], v[48:51], off offset:192
	v_lshl_add_u64 v[34:35], v[34:35], 0, s[4:5]
	s_barrier
	s_cbranch_vccz .LBB0_726

.LBB0_724:
	v_mul_f32_e32 v37, v37, v38
	v_exp_f32_e32 v37, v37
	s_waitcnt vmcnt(12)
	v_lshlrev_b32_e32 v44, 16, v12
	v_and_b32_e32 v45, 0xffff0000, v12
	v_and_b32_e32 v46, 0xffff0000, v13
	v_mul_f32_e32 v44, v37, v44
	v_mul_f32_e32 v45, v37, v45
	v_cvt_pk_bf16_f32 v44, v44, v45
	v_lshlrev_b32_e32 v45, 16, v13
	v_mul_f32_e32 v45, v37, v45
	v_mul_f32_e32 v46, v37, v46
	v_cvt_pk_bf16_f32 v45, v45, v46
	v_lshlrev_b32_e32 v46, 16, v14
	v_and_b32_e32 v47, 0xffff0000, v14
	v_mul_f32_e32 v46, v37, v46
	v_mul_f32_e32 v47, v37, v47
	v_cvt_pk_bf16_f32 v46, v46, v47
	v_lshlrev_b32_e32 v47, 16, v15
	v_mul_f32_e32 v47, v37, v47
	v_and_b32_e32 v48, 0xffff0000, v15
	v_mul_f32_e32 v48, v37, v48
	v_cvt_pk_bf16_f32 v47, v47, v48
	ds_write2_b64 v40, v[44:45], v[46:47] offset1:1
	v_lshlrev_b32_e32 v44, 16, v8
	v_and_b32_e32 v45, 0xffff0000, v8
	v_mul_f32_e32 v44, v37, v44
	v_mul_f32_e32 v45, v37, v45
	v_cvt_pk_bf16_f32 v44, v44, v45
	v_lshlrev_b32_e32 v45, 16, v9
	v_and_b32_e32 v46, 0xffff0000, v9
	v_mul_f32_e32 v45, v37, v45
	v_mul_f32_e32 v46, v37, v46
	v_cvt_pk_bf16_f32 v45, v45, v46
	v_lshlrev_b32_e32 v46, 16, v10
	v_and_b32_e32 v47, 0xffff0000, v10
	v_mul_f32_e32 v46, v37, v46
	v_mul_f32_e32 v47, v37, v47
	v_cvt_pk_bf16_f32 v46, v46, v47
	v_lshlrev_b32_e32 v47, 16, v11
	v_mul_f32_e32 v47, v37, v47
	v_and_b32_e32 v48, 0xffff0000, v11
	v_mul_f32_e32 v48, v37, v48
	v_cvt_pk_bf16_f32 v47, v47, v48
	ds_write2_b64 v40, v[44:45], v[46:47] offset0:2 offset1:3
	v_lshlrev_b32_e32 v44, 16, v4
	v_and_b32_e32 v45, 0xffff0000, v4
	v_mul_f32_e32 v44, v37, v44
	v_mul_f32_e32 v45, v37, v45
	v_cvt_pk_bf16_f32 v44, v44, v45
	v_lshlrev_b32_e32 v45, 16, v5
	v_and_b32_e32 v46, 0xffff0000, v5
	v_mul_f32_e32 v45, v37, v45
	v_mul_f32_e32 v46, v37, v46
	v_cvt_pk_bf16_f32 v45, v45, v46
	v_lshlrev_b32_e32 v46, 16, v6
	v_and_b32_e32 v47, 0xffff0000, v6
	v_mul_f32_e32 v46, v37, v46
	v_mul_f32_e32 v47, v37, v47
	v_cvt_pk_bf16_f32 v46, v46, v47
	v_lshlrev_b32_e32 v47, 16, v7
	v_mul_f32_e32 v47, v37, v47
	v_and_b32_e32 v48, 0xffff0000, v7
	v_mul_f32_e32 v48, v37, v48
	v_cvt_pk_bf16_f32 v47, v47, v48
	ds_write2_b64 v40, v[44:45], v[46:47] offset0:4 offset1:5
	v_lshlrev_b32_e32 v44, 16, v0
	v_and_b32_e32 v45, 0xffff0000, v0
	v_mul_f32_e32 v44, v37, v44
	v_mul_f32_e32 v45, v37, v45
	v_cvt_pk_bf16_f32 v44, v44, v45
	v_lshlrev_b32_e32 v45, 16, v1
	v_and_b32_e32 v46, 0xffff0000, v1
	v_mul_f32_e32 v45, v37, v45
	v_mul_f32_e32 v46, v37, v46
	v_cvt_pk_bf16_f32 v45, v45, v46
	v_lshlrev_b32_e32 v46, 16, v2
	v_and_b32_e32 v47, 0xffff0000, v2
	v_mul_f32_e32 v46, v37, v46
	v_mul_f32_e32 v47, v37, v47
	v_cvt_pk_bf16_f32 v46, v46, v47
	v_lshlrev_b32_e32 v47, 16, v3
	v_and_b32_e32 v48, 0xffff0000, v3
	v_mul_f32_e32 v47, v37, v47
	v_mul_f32_e32 v37, v37, v48
	v_cvt_pk_bf16_f32 v47, v47, v37
	v_add_u32_e32 v37, 0x9000, v40
	s_add_i32 s0, s0, 1
	s_waitcnt vmcnt(8)
	ds_write2_b64 v37, v[28:29], v[30:31] offset1:1
	v_add_u32_e32 v37, 0x9010, v40
	s_cmp_ge_i32 s0, s11
	ds_write2_b64 v37, v[24:25], v[26:27] offset1:1
	v_add_u32_e32 v37, 0x9020, v40
	s_cselect_b64 s[8:9], -1, 0
	ds_write2_b64 v37, v[20:21], v[22:23] offset1:1
	v_add_u32_e32 v37, 0x9030, v40
	s_and_b64 vcc, exec, s[8:9]
	ds_write2_b64 v40, v[44:45], v[46:47] offset0:6 offset1:7
	ds_write2_b64 v37, v[16:17], v[18:19] offset1:1
	s_cbranch_vccnz .LBB0_718
	s_ashr_i32 s6, s0, 6
	s_ashr_i32 s7, s6, 31
	s_and_b32 s14, s13, 0xf0000
	s_lshl_b64 s[6:7], s[6:7], 21
	s_lshl_b32 s14, s14, 1
	s_or_b32 s6, s6, s14
	s_add_u32 s14, s36, s6
	s_addc_u32 s15, s37, s7
	s_and_b32 s16, s12, 0x180
	s_lshl_b32 s16, s16, 1
	s_add_u32 s14, s14, s16
	s_addc_u32 s15, s15, 0
	s_add_u32 s6, s38, s6
	s_addc_u32 s7, s39, s7
	s_add_u32 s6, s6, s16
	s_addc_u32 s7, s7, 0
	v_lshl_add_u64 v[0:1], s[14:15], 0, v[32:33]
	v_mov_b32_e32 v37, v33
	v_lshl_add_u64 v[16:17], s[6:7], 0, v[32:33]
	v_lshl_add_u64 v[12:13], v[0:1], 0, v[36:37]
	v_lshl_add_u64 v[28:29], v[16:17], 0, v[36:37]
	global_load_dwordx4 v[0:3], v[12:13], off offset:48
	global_load_dwordx4 v[4:7], v[12:13], off offset:32
	global_load_dwordx4 v[8:11], v[12:13], off offset:16
	s_nop 0
	global_load_dwordx4 v[12:15], v[12:13], off
	s_nop 0
	global_load_dwordx4 v[16:19], v[28:29], off offset:48
	global_load_dwordx4 v[20:23], v[28:29], off offset:32
	global_load_dwordx4 v[24:27], v[28:29], off offset:16
	s_nop 0
	global_load_dwordx4 v[28:31], v[28:29], off
	s_branch .LBB0_718
